# GU GEMM K-loop: all 16 LDS-DMA loads per iteration use SGPR base + 32-bit VGPR offset instead of v_lshl_add_u64 64-bit addresses
# baseline (speedup 1.0000x reference)
; #define PG8_STAGE(bufoff, gbase, voff) do { _Pragma("unroll") for (int _i = 0; _i < 2; ++_i) \
;         __builtin_amdgcn_global_load_lds((const unsigned*)((const char*)(gbase) + (voff)[_i]), (LAS unsigned*)(lds + (bufoff) + ldsw + _i * 8192), 16, 0, 0); } while (0)
; #define PG8_LDA(dst, b, h) do { _Pragma("unroll") for (int m = 0; m < 4; ++m) _Pragma("unroll") for (int k = 0; k < 2; ++k) dst[m][k] = *(const LAS bf16x8*)(lds + PG8_SA(b, h) + aoff + m * 2048 + k * 1024); } while (0)
; #define PG8_LDB(dst, b, h) do { _Pragma("unroll") for (int n = 0; n < 2; ++n) _Pragma("unroll") for (int k = 0; k < 2; ++k) dst[n][k] = *(const LAS bf16x8*)(lds + PG8_SB(b, h) + boff + n * 2048 + k * 1024); } while (0)
; #define PG8_MMA(ai, bj, At, Bt) do { __builtin_amdgcn_s_setprio(1); _Pragma("unroll") for (int m = 0; m < 4; ++m) _Pragma("unroll") for (int n = 0; n < 2; ++n) _Pragma("unroll") for (int k = 0; k < 2; ++k) \
;         acc[ai][bj][m][n] = __builtin_amdgcn_mfma_f32_16x16x32_bf16(Bt[n][k], At[m][k], acc[ai][bj][m][n], 0, 0, 0); __builtin_amdgcn_s_setprio(0); } while (0)
; #define PG8_WAIT_V(n) asm volatile("s_waitcnt vmcnt(" #n ")" ::: "memory")
; #define PG8_WAIT_L(n) asm volatile("s_waitcnt lgkmcnt(" #n ")" ::: "memory")
; #define PG8_BAR __builtin_amdgcn_s_barrier()
; #define PG8_SCHED __builtin_amdgcn_sched_barrier(0)
; template <class Epi, class Sched, bool ALIGN_EPI>
; DI void gemm_phase(LAS unsigned char* lds, const Gemm g, const Sched& Sc, const Epi& E, const int tid) {
;     ...
;             PG8_LDB(B0, 0, 0); PG8_LDB(B1, 0, 1); PG8_SCHED; PG8_LDA(At, 0, 0); PG8_STAGE(PG8_SA(1, 1), a1 + hA, voffA);
;             PG8_WAIT_V(8); PG8_WAIT_L(0); PG8_BAR; PG8_MMA(0, 0, At, B0); PG8_MMA(0, 1, At, B1); PG8_BAR; PG8_SCHED;
;             PG8_LDA(At, 0, 1); PG8_STAGE(PG8_SB(0, 0), b2, voffB); PG8_STAGE(PG8_SB(0, 1), b2 + hB, voffB); PG8_STAGE(PG8_SA(0, 0), a2, voffA);
;             PG8_WAIT_V(8); PG8_WAIT_L(0); PG8_BAR; PG8_MMA(1, 0, At, B0); PG8_MMA(1, 1, At, B1); PG8_BAR; PG8_SCHED;
.LBB0_2634:
	v_add_u32_e32 v147, s39, v143
	ds_read_b128 v[148:151], v147
	ds_read_b128 v[152:155], v147 offset:1024
	ds_read_b128 v[156:159], v147 offset:2048
	ds_read_b128 v[160:163], v147 offset:3072
	v_add_u32_e32 v147, s48, v143
	ds_read_b128 v[164:167], v147
	ds_read_b128 v[168:171], v147 offset:1024
	ds_read_b128 v[172:175], v147 offset:2048
	ds_read_b128 v[176:179], v147 offset:3072
	s_add_u32 s42, s40, 0xfff80080
	s_addc_u32 s43, s41, -1
	s_cmp_eq_u32 s75, 28
	s_cselect_b32 s45, s23, s43
	s_cselect_b32 s44, s71, s42
	s_cselect_b32 s43, s19, s74
	s_cselect_b32 s42, s72, s73
	s_add_i32 m0, s51, 0xc000
	ds_read_b128 v[180:183], v146
	ds_read_b128 v[184:187], v146 offset:1024
	ds_read_b128 v[188:191], v146 offset:2048
	ds_read_b128 v[192:195], v146 offset:3072
	ds_read_b128 v[198:201], v146 offset:4096
	ds_read_b128 v[210:213], v146 offset:5120
	ds_read_b128 v[214:217], v146 offset:6144
	ds_read_b128 v[218:221], v146 offset:7168
	global_load_lds_dwordx4 v140, s[40:41]
	s_add_i32 m0, s51, 0xe000
	s_nop 0
	global_load_lds_dwordx4 v138, s[40:41]
	s_waitcnt vmcnt(8)
	s_waitcnt lgkmcnt(0)
	s_barrier
	s_setprio 1
	s_waitcnt lgkmcnt(0)
	v_mfma_f32_16x16x32_bf16 v[128:131], v[148:151], v[180:183], v[128:131]
	v_mfma_f32_16x16x32_bf16 v[124:127], v[156:159], v[180:183], v[124:127]
	v_mfma_f32_16x16x32_bf16 v[120:123], v[148:151], v[188:191], v[120:123]
	v_mfma_f32_16x16x32_bf16 v[116:119], v[156:159], v[188:191], v[116:119]
	v_mfma_f32_16x16x32_bf16 v[104:107], v[148:151], v[198:201], v[104:107]
	v_mfma_f32_16x16x32_bf16 v[100:103], v[156:159], v[198:201], v[100:103]
	v_mfma_f32_16x16x32_bf16 v[88:91], v[148:151], v[214:217], v[88:91]
	v_mfma_f32_16x16x32_bf16 v[84:87], v[156:159], v[214:217], v[84:87]
	v_mfma_f32_16x16x32_bf16 v[128:131], v[152:155], v[184:187], v[128:131]
	v_mfma_f32_16x16x32_bf16 v[124:127], v[160:163], v[184:187], v[124:127]
	v_mfma_f32_16x16x32_bf16 v[120:123], v[152:155], v[192:195], v[120:123]
	v_mfma_f32_16x16x32_bf16 v[116:119], v[160:163], v[192:195], v[116:119]
	v_mfma_f32_16x16x32_bf16 v[104:107], v[152:155], v[210:213], v[104:107]
	v_mfma_f32_16x16x32_bf16 v[100:103], v[160:163], v[210:213], v[100:103]
	v_mfma_f32_16x16x32_bf16 v[88:91], v[152:155], v[218:221], v[88:91]
	v_mfma_f32_16x16x32_bf16 v[84:87], v[160:163], v[218:221], v[84:87]
	s_setprio 0
	s_setprio 1
	v_mfma_f32_16x16x32_bf16 v[112:115], v[164:167], v[180:183], v[112:115]
	v_mfma_f32_16x16x32_bf16 v[108:111], v[172:175], v[180:183], v[108:111]
	v_mfma_f32_16x16x32_bf16 v[96:99], v[164:167], v[188:191], v[96:99]
	v_mfma_f32_16x16x32_bf16 v[92:95], v[172:175], v[188:191], v[92:95]
	v_mfma_f32_16x16x32_bf16 v[80:83], v[164:167], v[198:201], v[80:83]
	v_mfma_f32_16x16x32_bf16 v[76:79], v[172:175], v[198:201], v[76:79]
	v_mfma_f32_16x16x32_bf16 v[72:75], v[164:167], v[214:217], v[72:75]
	v_mfma_f32_16x16x32_bf16 v[68:71], v[172:175], v[214:217], v[68:71]
	v_mfma_f32_16x16x32_bf16 v[112:115], v[168:171], v[184:187], v[112:115]
	v_mfma_f32_16x16x32_bf16 v[108:111], v[176:179], v[184:187], v[108:111]
	v_mfma_f32_16x16x32_bf16 v[96:99], v[168:171], v[192:195], v[96:99]
	v_mfma_f32_16x16x32_bf16 v[92:95], v[176:179], v[192:195], v[92:95]
	v_mfma_f32_16x16x32_bf16 v[80:83], v[168:171], v[210:213], v[80:83]
	v_mfma_f32_16x16x32_bf16 v[76:79], v[176:179], v[210:213], v[76:79]
	v_mfma_f32_16x16x32_bf16 v[72:75], v[168:171], v[218:221], v[72:75]
	v_mfma_f32_16x16x32_bf16 v[68:71], v[176:179], v[218:221], v[68:71]
	s_setprio 0
	s_barrier
	s_mov_b32 m0, s46
	s_add_u32 s76, s42, 0x80000
	ds_read_b128 v[180:183], v146 offset:16384
	ds_read_b128 v[184:187], v146 offset:17408
	ds_read_b128 v[188:191], v146 offset:18432
	ds_read_b128 v[192:195], v146 offset:19456
	ds_read_b128 v[198:201], v146 offset:20480
	ds_read_b128 v[210:213], v146 offset:21504
	ds_read_b128 v[214:217], v146 offset:22528
	ds_read_b128 v[218:221], v146 offset:23552
	global_load_lds_dwordx4 v18, s[42:43]
	s_mov_b32 m0, s47
	s_addc_u32 s77, s43, 0
	global_load_lds_dwordx4 v132, s[42:43]
	s_mov_b32 m0, s49
	s_nop 0
	global_load_lds_dwordx4 v18, s[76:77]
	s_mov_b32 m0, s50
	s_nop 0
	global_load_lds_dwordx4 v132, s[76:77]
	s_mov_b32 m0, s51
	s_nop 0
	global_load_lds_dwordx4 v136, s[44:45]
	s_mov_b32 m0, s52
	s_nop 0
	global_load_lds_dwordx4 v134, s[44:45]
	s_waitcnt vmcnt(8)
	s_waitcnt lgkmcnt(0)
	s_barrier
	s_setprio 1
	s_waitcnt lgkmcnt(0)
	v_mfma_f32_16x16x32_bf16 v[64:67], v[148:151], v[180:183], v[64:67]
	v_mfma_f32_16x16x32_bf16 v[60:63], v[156:159], v[180:183], v[60:63]
	v_mfma_f32_16x16x32_bf16 v[56:59], v[148:151], v[188:191], v[56:59]
	v_mfma_f32_16x16x32_bf16 v[52:55], v[156:159], v[188:191], v[52:55]
	v_mfma_f32_16x16x32_bf16 v[40:43], v[148:151], v[198:201], v[40:43]
	v_mfma_f32_16x16x32_bf16 v[36:39], v[156:159], v[198:201], v[36:39]
	v_mfma_f32_16x16x32_bf16 v[24:27], v[148:151], v[214:217], v[24:27]
	v_mfma_f32_16x16x32_bf16 v[20:23], v[156:159], v[214:217], v[20:23]
	v_mfma_f32_16x16x32_bf16 v[64:67], v[152:155], v[184:187], v[64:67]
	v_mfma_f32_16x16x32_bf16 v[60:63], v[160:163], v[184:187], v[60:63]
	v_mfma_f32_16x16x32_bf16 v[56:59], v[152:155], v[192:195], v[56:59]
	v_mfma_f32_16x16x32_bf16 v[52:55], v[160:163], v[192:195], v[52:55]
	v_mfma_f32_16x16x32_bf16 v[40:43], v[152:155], v[210:213], v[40:43]
	v_mfma_f32_16x16x32_bf16 v[36:39], v[160:163], v[210:213], v[36:39]
	v_mfma_f32_16x16x32_bf16 v[24:27], v[152:155], v[218:221], v[24:27]
	v_mfma_f32_16x16x32_bf16 v[20:23], v[160:163], v[218:221], v[20:23]
	s_setprio 0
	s_setprio 1
	v_mfma_f32_16x16x32_bf16 v[48:51], v[164:167], v[180:183], v[48:51]
	v_mfma_f32_16x16x32_bf16 v[44:47], v[172:175], v[180:183], v[44:47]
	v_mfma_f32_16x16x32_bf16 v[32:35], v[164:167], v[188:191], v[32:35]
	v_mfma_f32_16x16x32_bf16 v[28:31], v[172:175], v[188:191], v[28:31]
	v_mfma_f32_16x16x32_bf16 v[14:17], v[164:167], v[198:201], v[14:17]
	v_mfma_f32_16x16x32_bf16 v[10:13], v[172:175], v[198:201], v[10:13]
	v_mfma_f32_16x16x32_bf16 v[6:9], v[164:167], v[214:217], v[6:9]
	v_mfma_f32_16x16x32_bf16 v[2:5], v[172:175], v[214:217], v[2:5]
	v_mfma_f32_16x16x32_bf16 v[48:51], v[168:171], v[184:187], v[48:51]
	v_mfma_f32_16x16x32_bf16 v[44:47], v[176:179], v[184:187], v[44:47]
	v_mfma_f32_16x16x32_bf16 v[32:35], v[168:171], v[192:195], v[32:35]
	v_mfma_f32_16x16x32_bf16 v[28:31], v[176:179], v[192:195], v[28:31]
	v_mfma_f32_16x16x32_bf16 v[14:17], v[168:171], v[210:213], v[14:17]
	v_mfma_f32_16x16x32_bf16 v[10:13], v[176:179], v[210:213], v[10:13]
	v_mfma_f32_16x16x32_bf16 v[6:9], v[168:171], v[218:221], v[6:9]
	v_mfma_f32_16x16x32_bf16 v[2:5], v[176:179], v[218:221], v[2:5]
	s_setprio 0
	s_barrier
; #define PG8_STAGE(bufoff, gbase, voff) do { _Pragma("unroll") for (int _i = 0; _i < 2; ++_i) \
;         __builtin_amdgcn_global_load_lds((const unsigned*)((const char*)(gbase) + (voff)[_i]), (LAS unsigned*)(lds + (bufoff) + ldsw + _i * 8192), 16, 0, 0); } while (0)
; #define PG8_LDA(dst, b, h) do { _Pragma("unroll") for (int m = 0; m < 4; ++m) _Pragma("unroll") for (int k = 0; k < 2; ++k) dst[m][k] = *(const LAS bf16x8*)(lds + PG8_SA(b, h) + aoff + m * 2048 + k * 1024); } while (0)
; #define PG8_LDB(dst, b, h) do { _Pragma("unroll") for (int n = 0; n < 2; ++n) _Pragma("unroll") for (int k = 0; k < 2; ++k) dst[n][k] = *(const LAS bf16x8*)(lds + PG8_SB(b, h) + boff + n * 2048 + k * 1024); } while (0)
; #define PG8_MMA(ai, bj, At, Bt) do { __builtin_amdgcn_s_setprio(1); _Pragma("unroll") for (int m = 0; m < 4; ++m) _Pragma("unroll") for (int n = 0; n < 2; ++n) _Pragma("unroll") for (int k = 0; k < 2; ++k) \
;         acc[ai][bj][m][n] = __builtin_amdgcn_mfma_f32_16x16x32_bf16(Bt[n][k], At[m][k], acc[ai][bj][m][n], 0, 0, 0); __builtin_amdgcn_s_setprio(0); } while (0)
; #define PG8_WAIT_V(n) asm volatile("s_waitcnt vmcnt(" #n ")" ::: "memory")
; #define PG8_WAIT_L(n) asm volatile("s_waitcnt lgkmcnt(" #n ")" ::: "memory")
; #define PG8_BAR __builtin_amdgcn_s_barrier()
; #define PG8_SCHED __builtin_amdgcn_sched_barrier(0)
; template <class Epi, class Sched, bool ALIGN_EPI>
; DI void gemm_phase(LAS unsigned char* lds, const Gemm g, const Sched& Sc, const Epi& E, const int tid) {
;     ...
;             PG8_LDB(B0, 1, 0); PG8_LDB(B1, 1, 1); PG8_SCHED; PG8_LDA(At, 1, 0); PG8_STAGE(PG8_SA(0, 1), a2 + hA, voffA);
;             PG8_WAIT_V(8); PG8_WAIT_L(0); PG8_BAR; PG8_MMA(0, 0, At, B0); PG8_MMA(0, 1, At, B1); PG8_BAR; PG8_SCHED;
;             PG8_LDA(At, 1, 1); PG8_STAGE(PG8_SB(1, 0), b3, voffB); PG8_STAGE(PG8_SB(1, 1), b3 + hB, voffB); PG8_STAGE(PG8_SA(1, 0), a3, voffA);
;             PG8_WAIT_V(8); PG8_WAIT_L(0); PG8_BAR; PG8_MMA(1, 0, At, B0); PG8_MMA(1, 1, At, B1); PG8_BAR; PG8_SCHED;
	v_add_u32_e32 v147, s55, v143
	ds_read_b128 v[148:151], v147
	ds_read_b128 v[152:155], v147 offset:1024
	ds_read_b128 v[156:159], v147 offset:2048
	ds_read_b128 v[160:163], v147 offset:3072
	v_add_u32_e32 v147, s64, v143
	ds_read_b128 v[164:167], v147
	ds_read_b128 v[168:171], v147 offset:1024
	ds_read_b128 v[172:175], v147 offset:2048
	ds_read_b128 v[176:179], v147 offset:3072
	s_add_u32 s44, s44, 0x80000
	s_addc_u32 s45, s45, 0
	s_mov_b32 m0, s53
	ds_read_b128 v[180:183], v146 offset:32768
	ds_read_b128 v[184:187], v146 offset:33792
	ds_read_b128 v[188:191], v146 offset:34816
	ds_read_b128 v[192:195], v146 offset:35840
	ds_read_b128 v[198:201], v146 offset:36864
	ds_read_b128 v[210:213], v146 offset:37888
	ds_read_b128 v[214:217], v146 offset:38912
	ds_read_b128 v[218:221], v146 offset:39936
	global_load_lds_dwordx4 v136, s[44:45]
	s_mov_b32 m0, s54
	s_nop 0
	global_load_lds_dwordx4 v134, s[44:45]
	s_waitcnt vmcnt(8)
	s_waitcnt lgkmcnt(0)
	s_barrier
	s_setprio 1
	s_waitcnt lgkmcnt(0)
	v_mfma_f32_16x16x32_bf16 v[128:131], v[148:151], v[180:183], v[128:131]
	v_mfma_f32_16x16x32_bf16 v[124:127], v[156:159], v[180:183], v[124:127]
	v_mfma_f32_16x16x32_bf16 v[120:123], v[148:151], v[188:191], v[120:123]
	v_mfma_f32_16x16x32_bf16 v[116:119], v[156:159], v[188:191], v[116:119]
	v_mfma_f32_16x16x32_bf16 v[104:107], v[148:151], v[198:201], v[104:107]
	v_mfma_f32_16x16x32_bf16 v[100:103], v[156:159], v[198:201], v[100:103]
	v_mfma_f32_16x16x32_bf16 v[88:91], v[148:151], v[214:217], v[88:91]
	v_mfma_f32_16x16x32_bf16 v[84:87], v[156:159], v[214:217], v[84:87]
	v_mfma_f32_16x16x32_bf16 v[128:131], v[152:155], v[184:187], v[128:131]
	v_mfma_f32_16x16x32_bf16 v[124:127], v[160:163], v[184:187], v[124:127]
	v_mfma_f32_16x16x32_bf16 v[120:123], v[152:155], v[192:195], v[120:123]
	v_mfma_f32_16x16x32_bf16 v[116:119], v[160:163], v[192:195], v[116:119]
	v_mfma_f32_16x16x32_bf16 v[104:107], v[152:155], v[210:213], v[104:107]
	v_mfma_f32_16x16x32_bf16 v[100:103], v[160:163], v[210:213], v[100:103]
	v_mfma_f32_16x16x32_bf16 v[88:91], v[152:155], v[218:221], v[88:91]
	v_mfma_f32_16x16x32_bf16 v[84:87], v[160:163], v[218:221], v[84:87]
	s_setprio 0
	s_setprio 1
	v_mfma_f32_16x16x32_bf16 v[112:115], v[164:167], v[180:183], v[112:115]
	v_mfma_f32_16x16x32_bf16 v[108:111], v[172:175], v[180:183], v[108:111]
	v_mfma_f32_16x16x32_bf16 v[96:99], v[164:167], v[188:191], v[96:99]
	v_mfma_f32_16x16x32_bf16 v[92:95], v[172:175], v[188:191], v[92:95]
	v_mfma_f32_16x16x32_bf16 v[80:83], v[164:167], v[198:201], v[80:83]
	v_mfma_f32_16x16x32_bf16 v[76:79], v[172:175], v[198:201], v[76:79]
	v_mfma_f32_16x16x32_bf16 v[72:75], v[164:167], v[214:217], v[72:75]
	v_mfma_f32_16x16x32_bf16 v[68:71], v[172:175], v[214:217], v[68:71]
	v_mfma_f32_16x16x32_bf16 v[112:115], v[168:171], v[184:187], v[112:115]
	v_mfma_f32_16x16x32_bf16 v[108:111], v[176:179], v[184:187], v[108:111]
	v_mfma_f32_16x16x32_bf16 v[96:99], v[168:171], v[192:195], v[96:99]
	v_mfma_f32_16x16x32_bf16 v[92:95], v[176:179], v[192:195], v[92:95]
	v_mfma_f32_16x16x32_bf16 v[80:83], v[168:171], v[210:213], v[80:83]
	v_mfma_f32_16x16x32_bf16 v[76:79], v[176:179], v[210:213], v[76:79]
	v_mfma_f32_16x16x32_bf16 v[72:75], v[168:171], v[218:221], v[72:75]
	v_mfma_f32_16x16x32_bf16 v[68:71], v[176:179], v[218:221], v[68:71]
	s_setprio 0
	s_barrier
	s_mov_b32 m0, s56
	s_add_u32 s76, s42, s60
	s_addc_u32 s77, s43, s61
	s_add_u32 s42, s42, 0x80080
	ds_read_b128 v[180:183], v146 offset:49152
	ds_read_b128 v[184:187], v146 offset:50176
	ds_read_b128 v[188:191], v146 offset:51200
	ds_read_b128 v[192:195], v146 offset:52224
	ds_read_b128 v[198:201], v146 offset:53248
	ds_read_b128 v[210:213], v146 offset:54272
	ds_read_b128 v[214:217], v146 offset:55296
	ds_read_b128 v[218:221], v146 offset:56320
	global_load_lds_dwordx4 v18, s[76:77]
	s_mov_b32 m0, s57
	s_addc_u32 s43, s43, 0
	global_load_lds_dwordx4 v132, s[76:77]
	s_mov_b32 m0, s65
	s_nop 0
	global_load_lds_dwordx4 v18, s[42:43]
	s_mov_b32 m0, s66
	s_nop 0
	global_load_lds_dwordx4 v132, s[42:43]
	s_add_u32 s76, s44, 0xfff80080
	s_addc_u32 s77, s45, -1
	s_mov_b32 m0, s62
	s_nop 0
	global_load_lds_dwordx4 v136, s[76:77]
	s_mov_b32 m0, s63
	s_nop 0
	global_load_lds_dwordx4 v134, s[76:77]
	s_waitcnt vmcnt(8)
	s_waitcnt lgkmcnt(0)
	s_barrier
	s_setprio 1
	s_waitcnt lgkmcnt(0)
	v_mfma_f32_16x16x32_bf16 v[64:67], v[148:151], v[180:183], v[64:67]
	v_mfma_f32_16x16x32_bf16 v[60:63], v[156:159], v[180:183], v[60:63]
	v_mfma_f32_16x16x32_bf16 v[56:59], v[148:151], v[188:191], v[56:59]
	v_mfma_f32_16x16x32_bf16 v[52:55], v[156:159], v[188:191], v[52:55]
	v_mfma_f32_16x16x32_bf16 v[40:43], v[148:151], v[198:201], v[40:43]
	v_mfma_f32_16x16x32_bf16 v[36:39], v[156:159], v[198:201], v[36:39]
	v_mfma_f32_16x16x32_bf16 v[24:27], v[148:151], v[214:217], v[24:27]
	v_mfma_f32_16x16x32_bf16 v[20:23], v[156:159], v[214:217], v[20:23]
	v_mfma_f32_16x16x32_bf16 v[64:67], v[152:155], v[184:187], v[64:67]
	v_mfma_f32_16x16x32_bf16 v[60:63], v[160:163], v[184:187], v[60:63]
	v_mfma_f32_16x16x32_bf16 v[56:59], v[152:155], v[192:195], v[56:59]
	v_mfma_f32_16x16x32_bf16 v[52:55], v[160:163], v[192:195], v[52:55]
	v_mfma_f32_16x16x32_bf16 v[40:43], v[152:155], v[210:213], v[40:43]
	v_mfma_f32_16x16x32_bf16 v[36:39], v[160:163], v[210:213], v[36:39]
	v_mfma_f32_16x16x32_bf16 v[24:27], v[152:155], v[218:221], v[24:27]
	v_mfma_f32_16x16x32_bf16 v[20:23], v[160:163], v[218:221], v[20:23]
	s_setprio 0
	s_setprio 1
	v_mfma_f32_16x16x32_bf16 v[48:51], v[164:167], v[180:183], v[48:51]
	v_mfma_f32_16x16x32_bf16 v[44:47], v[172:175], v[180:183], v[44:47]
	v_mfma_f32_16x16x32_bf16 v[32:35], v[164:167], v[188:191], v[32:35]
	v_mfma_f32_16x16x32_bf16 v[28:31], v[172:175], v[188:191], v[28:31]
	v_mfma_f32_16x16x32_bf16 v[14:17], v[164:167], v[198:201], v[14:17]
	v_mfma_f32_16x16x32_bf16 v[10:13], v[172:175], v[198:201], v[10:13]
	v_mfma_f32_16x16x32_bf16 v[6:9], v[164:167], v[214:217], v[6:9]
	v_mfma_f32_16x16x32_bf16 v[2:5], v[172:175], v[214:217], v[2:5]
	v_mfma_f32_16x16x32_bf16 v[48:51], v[168:171], v[184:187], v[48:51]
	v_mfma_f32_16x16x32_bf16 v[44:47], v[176:179], v[184:187], v[44:47]
	v_mfma_f32_16x16x32_bf16 v[32:35], v[168:171], v[192:195], v[32:35]
	v_mfma_f32_16x16x32_bf16 v[28:31], v[176:179], v[192:195], v[28:31]
	v_mfma_f32_16x16x32_bf16 v[14:17], v[168:171], v[210:213], v[14:17]
	v_mfma_f32_16x16x32_bf16 v[10:13], v[176:179], v[210:213], v[10:13]
	v_mfma_f32_16x16x32_bf16 v[6:9], v[168:171], v[218:221], v[6:9]
	v_mfma_f32_16x16x32_bf16 v[2:5], v[176:179], v[218:221], v[2:5]
	s_setprio 0
	s_barrier
	s_add_i32 s75, s75, 2
	s_add_u32 s73, s73, 0x100
	s_addc_u32 s74, s74, 0
	s_add_u32 s40, s40, 0x100
	s_addc_u32 s41, s41, 0
	s_cmp_gt_u32 s75, 29
	s_cbranch_scc0 .LBB0_2634
	s_and_b64 vcc, exec, s[16:17]
	s_cbranch_vccz .LBB0_2637
	s_barrier
